# GEMM K-loop: B DMAs moved inside the second MFMA group
# speedup vs baseline: 1.0058x; 1.0058x over previous
.LBB0_246:
	s_add_i32 s10, s7, 0xffffa000
	s_cmp_lg_u32 s7, 0
	s_cselect_b32 s12, s10, 0xc000
	v_add_u32_e32 v131, s7, v150
	s_waitcnt vmcnt(6)
	s_barrier
	v_add_u32_e32 v133, s7, v149
	ds_read_b128 v[154:157], v131 offset:0
	ds_read_b128 v[158:161], v131 offset:0x400
	ds_read_b128 v[162:165], v131 offset:0x800
	ds_read_b128 v[166:169], v131 offset:0xc00
	v_add_u32_e32 v131, s12, v147
	ds_read_b128 v[170:173], v133 offset:0
	ds_read_b128 v[174:177], v133 offset:0x400
	ds_read_b128 v[178:181], v133 offset:0x800
	ds_read_b128 v[200:203], v133 offset:0xc00
	s_add_u32 s10, s8, s50
	s_addc_u32 s11, s9, s51
	v_readfirstlane_b32 s13, v131
	s_add_u32 s64, s5, s100
	s_addc_u32 s65, s6, 0
	s_sub_i32 s68, s13, s12
	s_lshr_b32 s68, s68, 1
	s_add_i32 s68, s68, s12
	s_addk_i32 s68, 0x4000
	s_waitcnt lgkmcnt(0)
	s_nop 0
	v_mfma_f32_16x16x32_bf16 v[126:129], v[154:157], v[170:173], v[126:129]
	ds_read_b128 v[204:207], v133 offset:0x1000
	v_mfma_f32_16x16x32_bf16 v[122:125], v[154:157], v[174:177], v[122:125]
	ds_read_b128 v[208:211], v133 offset:0x1400
	v_mfma_f32_16x16x32_bf16 v[118:121], v[154:157], v[178:181], v[118:121]
	ds_read_b128 v[212:215], v133 offset:0x1800
	v_mfma_f32_16x16x32_bf16 v[114:117], v[154:157], v[200:203], v[114:117]
	ds_read_b128 v[216:219], v133 offset:0x1c00
	v_mfma_f32_16x16x32_bf16 v[110:113], v[158:161], v[170:173], v[110:113]
	s_mov_b32 m0, s13
	s_nop 0
	global_load_lds_dwordx4 v0, s[10:11]
	v_mfma_f32_16x16x32_bf16 v[102:105], v[158:161], v[174:177], v[102:105]
	v_mfma_f32_16x16x32_bf16 v[94:97], v[158:161], v[178:181], v[94:97]
	v_mfma_f32_16x16x32_bf16 v[86:89], v[158:161], v[200:203], v[86:89]
	s_add_u32 m0, s13, 0x400
	s_nop 0
	global_load_lds_dwordx4 v130, s[10:11]
	v_mfma_f32_16x16x32_bf16 v[78:81], v[162:165], v[170:173], v[78:81]
	v_mfma_f32_16x16x32_bf16 v[70:73], v[162:165], v[174:177], v[70:73]
	v_mfma_f32_16x16x32_bf16 v[62:65], v[162:165], v[178:181], v[62:65]
	s_add_u32 m0, s13, 0x800
	s_nop 0
	global_load_lds_dwordx4 v132, s[10:11]
	v_mfma_f32_16x16x32_bf16 v[54:57], v[162:165], v[200:203], v[54:57]
	v_mfma_f32_16x16x32_bf16 v[46:49], v[166:169], v[170:173], v[46:49]
	v_mfma_f32_16x16x32_bf16 v[38:41], v[166:169], v[174:177], v[38:41]
	s_add_u32 m0, s13, 0xc00
	s_nop 0
	global_load_lds_dwordx4 v136, s[10:11]
	v_mfma_f32_16x16x32_bf16 v[30:33], v[166:169], v[178:181], v[30:33]
	v_mfma_f32_16x16x32_bf16 v[22:25], v[166:169], v[200:203], v[22:25]
	s_waitcnt lgkmcnt(0)
	s_nop 0
	v_mfma_f32_16x16x32_bf16 v[106:109], v[154:157], v[204:207], v[106:109]
	v_mfma_f32_16x16x32_bf16 v[98:101], v[154:157], v[208:211], v[98:101]
	v_mfma_f32_16x16x32_bf16 v[90:93], v[154:157], v[212:215], v[90:93]
	s_mov_b32 m0, s68
	s_nop 0
	global_load_lds_dwordx4 v138, s[64:65]
	v_mfma_f32_16x16x32_bf16 v[82:85], v[154:157], v[216:219], v[82:85]
	v_mfma_f32_16x16x32_bf16 v[74:77], v[158:161], v[204:207], v[74:77]
	v_mfma_f32_16x16x32_bf16 v[66:69], v[158:161], v[208:211], v[66:69]
	v_mfma_f32_16x16x32_bf16 v[58:61], v[158:161], v[212:215], v[58:61]
	v_mfma_f32_16x16x32_bf16 v[50:53], v[158:161], v[216:219], v[50:53]
	v_mfma_f32_16x16x32_bf16 v[42:45], v[162:165], v[204:207], v[42:45]
	s_add_u32 m0, s68, 0x400
	s_nop 0
	global_load_lds_dwordx4 v140, s[64:65]
	v_mfma_f32_16x16x32_bf16 v[34:37], v[162:165], v[208:211], v[34:37]
	v_mfma_f32_16x16x32_bf16 v[26:29], v[162:165], v[212:215], v[26:29]
	v_mfma_f32_16x16x32_bf16 v[18:21], v[162:165], v[216:219], v[18:21]
	v_mfma_f32_16x16x32_bf16 v[14:17], v[166:169], v[204:207], v[14:17]
	v_mfma_f32_16x16x32_bf16 v[10:13], v[166:169], v[208:211], v[10:13]
	v_mfma_f32_16x16x32_bf16 v[6:9], v[166:169], v[212:215], v[6:9]
	v_mfma_f32_16x16x32_bf16 v[2:5], v[166:169], v[216:219], v[2:5]
	s_add_i32 s10, s7, 0x6000
	s_cmpk_lg_u32 s7, 0xc000
	s_cselect_b32 s7, s10, 0
	s_addk_i32 s100, 0x400
	s_add_u32 s50, s50, s60
	s_addc_u32 s51, s51, 0
	s_cmpk_lg_i32 s100, 0x7800
	s_cbranch_scc1 .LBB0_246
	s_waitcnt vmcnt(6)
	s_barrier
	v_add_u32_e32 v0, s7, v150
	v_add_u32_e32 v140, s7, v149
	ds_read_b128 v[130:133], v0 offset:0
	ds_read_b128 v[136:139], v0 offset:0x400
	ds_read_b128 v[154:157], v0 offset:0x800
	ds_read_b128 v[158:161], v0 offset:0xc00
	ds_read_b128 v[162:165], v140 offset:0
	ds_read_b128 v[166:169], v140 offset:0x400
	ds_read_b128 v[170:173], v140 offset:0x800
	ds_read_b128 v[174:177], v140 offset:0xc00
	ds_read_b128 v[178:181], v140 offset:0x1000
	ds_read_b128 v[200:203], v140 offset:0x1400
	ds_read_b128 v[204:207], v140 offset:0x1800
	ds_read_b128 v[208:211], v140 offset:0x1c00
	s_lshl_b32 s49, s4, 8
	s_waitcnt lgkmcnt(4)
	s_nop 0
	v_mfma_f32_16x16x32_bf16 v[126:129], v[130:133], v[162:165], v[126:129]
	v_mfma_f32_16x16x32_bf16 v[118:121], v[130:133], v[170:173], v[118:121]
	v_mfma_f32_16x16x32_bf16 v[114:117], v[130:133], v[174:177], v[114:117]
	v_mfma_f32_16x16x32_bf16 v[110:113], v[136:139], v[162:165], v[110:113]
	v_mfma_f32_16x16x32_bf16 v[102:105], v[136:139], v[166:169], v[102:105]
	v_mfma_f32_16x16x32_bf16 v[94:97], v[136:139], v[170:173], v[94:97]
	v_mfma_f32_16x16x32_bf16 v[86:89], v[136:139], v[174:177], v[86:89]
	v_mfma_f32_16x16x32_bf16 v[70:73], v[154:157], v[166:169], v[70:73]
	v_mfma_f32_16x16x32_bf16 v[62:65], v[154:157], v[170:173], v[62:65]
	v_mfma_f32_16x16x32_bf16 v[54:57], v[154:157], v[174:177], v[54:57]
	v_mfma_f32_16x16x32_bf16 v[46:49], v[158:161], v[162:165], v[46:49]
	v_mfma_f32_16x16x32_bf16 v[38:41], v[158:161], v[166:169], v[38:41]
	v_mfma_f32_16x16x32_bf16 v[30:33], v[158:161], v[170:173], v[30:33]
	v_mfma_f32_16x16x32_bf16 v[22:25], v[158:161], v[174:177], v[22:25]
	v_mfma_f32_16x16x32_bf16 v[212:215], v[130:133], v[166:169], v[122:125]
	v_mfma_f32_16x16x32_bf16 v[216:219], v[154:157], v[162:165], v[78:81]
	s_waitcnt lgkmcnt(0)
	s_nop 0
	v_mfma_f32_16x16x32_bf16 v[174:177], v[136:139], v[178:181], v[74:77]
	v_mfma_f32_16x16x32_bf16 v[220:223], v[136:139], v[200:203], v[66:69]
	v_mfma_f32_16x16x32_bf16 v[224:227], v[136:139], v[204:207], v[58:61]
	v_mfma_f32_16x16x32_bf16 v[50:53], v[136:139], v[208:211], v[50:53]
	v_mfma_f32_16x16x32_bf16 v[136:139], v[154:157], v[178:181], v[42:45]
	v_mfma_f32_16x16x32_bf16 v[34:37], v[154:157], v[200:203], v[34:37]
	v_mfma_f32_16x16x32_bf16 v[6:9], v[158:161], v[204:207], v[6:9]
	v_mfma_f32_16x16x32_bf16 v[162:165], v[130:133], v[178:181], v[106:109]
	v_mfma_f32_16x16x32_bf16 v[166:169], v[130:133], v[200:203], v[98:101]
	v_mfma_f32_16x16x32_bf16 v[170:173], v[130:133], v[204:207], v[90:93]
	v_mfma_f32_16x16x32_bf16 v[130:133], v[130:133], v[208:211], v[82:85]
	v_mfma_f32_16x16x32_bf16 v[228:231], v[154:157], v[204:207], v[26:29]
	v_mfma_f32_16x16x32_bf16 v[154:157], v[154:157], v[208:211], v[18:21]
	v_mfma_f32_16x16x32_bf16 v[178:181], v[158:161], v[178:181], v[14:17]
	v_mfma_f32_16x16x32_bf16 v[200:203], v[158:161], v[200:203], v[10:13]
	v_mfma_f32_16x16x32_bf16 v[158:161], v[158:161], v[208:211], v[2:5]
	s_waitcnt vmcnt(0)
	s_barrier
	ds_read_b128 v[2:5], v151 offset:0
	ds_read_b128 v[14:17], v151 offset:0x400
	ds_read_b128 v[204:207], v151 offset:0x800
	ds_read_b128 v[208:211], v151 offset:0xc00
	ds_read_b128 v[10:13], v152 offset:0
	ds_read_b128 v[18:21], v152 offset:0x400
	ds_read_b128 v[26:29], v152 offset:0x800
	ds_read_b128 v[42:45], v152 offset:0xc00
	ds_read_b128 v[232:235], v152 offset:0x1000
	ds_read_b128 v[236:239], v152 offset:0x1400
	ds_read_b128 v[240:243], v152 offset:0x1800
	ds_read_b128 v[244:247], v152 offset:0x1c00
	s_nop 0
	s_waitcnt lgkmcnt(4)
	s_nop 0
	v_mfma_f32_16x16x32_bf16 v[122:125], v[2:5], v[10:13], v[126:129]
	v_mfma_f32_16x16x32_bf16 v[106:109], v[2:5], v[18:21], v[212:215]
	v_mfma_f32_16x16x32_bf16 v[90:93], v[2:5], v[26:29], v[118:121]
	v_mfma_f32_16x16x32_bf16 v[74:77], v[2:5], v[42:45], v[114:117]
	v_mfma_f32_16x16x32_bf16 v[126:129], v[14:17], v[10:13], v[110:113]
	v_mfma_f32_16x16x32_bf16 v[110:113], v[14:17], v[18:21], v[102:105]
	v_mfma_f32_16x16x32_bf16 v[94:97], v[14:17], v[26:29], v[94:97]
	v_mfma_f32_16x16x32_bf16 v[78:81], v[14:17], v[42:45], v[86:89]
	v_mfma_f32_16x16x32_bf16 v[114:117], v[204:207], v[10:13], v[216:219]
	v_mfma_f32_16x16x32_bf16 v[98:101], v[204:207], v[18:21], v[70:73]
	v_mfma_f32_16x16x32_bf16 v[82:85], v[204:207], v[26:29], v[62:65]
	v_mfma_f32_16x16x32_bf16 v[66:69], v[204:207], v[42:45], v[54:57]
	v_mfma_f32_16x16x32_bf16 v[118:121], v[208:211], v[10:13], v[46:49]
	v_mfma_f32_16x16x32_bf16 v[102:105], v[208:211], v[18:21], v[38:41]
	v_mfma_f32_16x16x32_bf16 v[86:89], v[208:211], v[26:29], v[30:33]
	v_mfma_f32_16x16x32_bf16 v[70:73], v[208:211], v[42:45], v[22:25]
	s_waitcnt lgkmcnt(0)
	s_nop 0
	v_mfma_f32_16x16x32_bf16 v[58:61], v[2:5], v[232:235], v[162:165]
	v_mfma_f32_16x16x32_bf16 v[42:45], v[2:5], v[236:239], v[166:169]
	v_mfma_f32_16x16x32_bf16 v[26:29], v[2:5], v[240:243], v[170:173]
	v_mfma_f32_16x16x32_bf16 v[10:13], v[2:5], v[244:247], v[130:133]
	v_mfma_f32_16x16x32_bf16 v[62:65], v[14:17], v[232:235], v[174:177]
	v_mfma_f32_16x16x32_bf16 v[46:49], v[14:17], v[236:239], v[220:223]
	v_mfma_f32_16x16x32_bf16 v[30:33], v[14:17], v[240:243], v[224:227]
	v_mfma_f32_16x16x32_bf16 v[14:17], v[14:17], v[244:247], v[50:53]
	v_mfma_f32_16x16x32_bf16 v[50:53], v[204:207], v[232:235], v[136:139]
	v_mfma_f32_16x16x32_bf16 v[34:37], v[204:207], v[236:239], v[34:37]
	v_mfma_f32_16x16x32_bf16 v[18:21], v[204:207], v[240:243], v[228:231]
	v_mfma_f32_16x16x32_bf16 v[2:5], v[204:207], v[244:247], v[154:157]
	v_mfma_f32_16x16x32_bf16 v[54:57], v[208:211], v[232:235], v[178:181]
	v_mfma_f32_16x16x32_bf16 v[38:41], v[208:211], v[236:239], v[200:203]
	v_mfma_f32_16x16x32_bf16 v[22:25], v[208:211], v[240:243], v[6:9]
	v_mfma_f32_16x16x32_bf16 v[6:9], v[208:211], v[244:247], v[158:161]
	v_mov_b32_e32 v136, v134
	s_mov_b64 s[50:51], -1
	s_and_b64 vcc, exec, s[22:23]
	s_barrier
	s_cbranch_vccz .LBB0_264
	s_and_b64 vcc, exec, s[0:1]
	s_cbranch_vccz .LBB0_250
	v_lshrrev_b32_e32 v0, 6, v136
	v_mul_lo_u32 v137, v0, s14
	v_and_b32_e32 v130, 15, v136
	v_and_or_b32 v0, v136, 48, v137
	s_movk_i32 s4, 0x90
	v_mad_u32_u24 v0, v130, s4, v0
	v_cvt_pk_bf16_f32 v130, v122, v123
	v_cvt_pk_bf16_f32 v131, v124, v125
	v_cvt_pk_bf16_f32 v132, v126, v127
	v_cvt_pk_bf16_f32 v133, v128, v129
	s_waitcnt vmcnt(0)
	ds_write_b128 v0, v[130:133]
	v_cvt_pk_bf16_f32 v130, v114, v115
	v_cvt_pk_bf16_f32 v131, v116, v117
	v_cvt_pk_bf16_f32 v132, v118, v119
	v_cvt_pk_bf16_f32 v133, v120, v121
	ds_write_b128 v0, v[130:133] offset:64
	v_cvt_pk_bf16_f32 v130, v106, v107
	v_cvt_pk_bf16_f32 v131, v108, v109
	v_cvt_pk_bf16_f32 v132, v110, v111
	v_cvt_pk_bf16_f32 v133, v112, v113
	ds_write_b128 v0, v[130:133] offset:2304
	v_cvt_pk_bf16_f32 v130, v98, v99
	v_cvt_pk_bf16_f32 v131, v100, v101
	v_cvt_pk_bf16_f32 v132, v102, v103
	v_cvt_pk_bf16_f32 v133, v104, v105
	ds_write_b128 v0, v[130:133] offset:2368
	v_cvt_pk_bf16_f32 v130, v90, v91
	v_cvt_pk_bf16_f32 v131, v92, v93
	v_cvt_pk_bf16_f32 v132, v94, v95
	v_cvt_pk_bf16_f32 v133, v96, v97
	ds_write_b128 v0, v[130:133] offset:4608
	v_cvt_pk_bf16_f32 v130, v82, v83
	v_cvt_pk_bf16_f32 v131, v84, v85
	v_cvt_pk_bf16_f32 v132, v86, v87
	v_cvt_pk_bf16_f32 v133, v88, v89
	ds_write_b128 v0, v[130:133] offset:4672
	v_cvt_pk_bf16_f32 v130, v74, v75
	v_cvt_pk_bf16_f32 v131, v76, v77
	v_cvt_pk_bf16_f32 v132, v78, v79
	v_cvt_pk_bf16_f32 v133, v80, v81
	ds_write_b128 v0, v[130:133] offset:6912
	v_cvt_pk_bf16_f32 v130, v66, v67
	v_cvt_pk_bf16_f32 v131, v68, v69
	v_cvt_pk_bf16_f32 v132, v70, v71
	v_cvt_pk_bf16_f32 v133, v72, v73
	ds_write_b128 v0, v[130:133] offset:6976
	v_cvt_pk_bf16_f32 v130, v58, v59
	v_cvt_pk_bf16_f32 v131, v60, v61
	v_cvt_pk_bf16_f32 v132, v62, v63
	v_cvt_pk_bf16_f32 v133, v64, v65
	ds_write_b128 v0, v[130:133] offset:9216
	v_cvt_pk_bf16_f32 v130, v50, v51
	v_cvt_pk_bf16_f32 v131, v52, v53
	v_cvt_pk_bf16_f32 v132, v54, v55
	v_cvt_pk_bf16_f32 v133, v56, v57
	ds_write_b128 v0, v[130:133] offset:9280
	v_cvt_pk_bf16_f32 v130, v42, v43
	v_cvt_pk_bf16_f32 v131, v44, v45
	v_cvt_pk_bf16_f32 v132, v46, v47
	v_cvt_pk_bf16_f32 v133, v48, v49
	ds_write_b128 v0, v[130:133] offset:11520
	v_cvt_pk_bf16_f32 v130, v34, v35
	v_cvt_pk_bf16_f32 v131, v36, v37
	v_cvt_pk_bf16_f32 v132, v38, v39
	v_cvt_pk_bf16_f32 v133, v40, v41
	ds_write_b128 v0, v[130:133] offset:11584
	v_cvt_pk_bf16_f32 v130, v26, v27
	v_cvt_pk_bf16_f32 v131, v28, v29
	v_cvt_pk_bf16_f32 v132, v30, v31
	v_cvt_pk_bf16_f32 v133, v32, v33
	ds_write_b128 v0, v[130:133] offset:13824
	v_cvt_pk_bf16_f32 v130, v18, v19
	v_cvt_pk_bf16_f32 v131, v20, v21
	v_cvt_pk_bf16_f32 v132, v22, v23
	v_cvt_pk_bf16_f32 v133, v24, v25
	ds_write_b128 v0, v[130:133] offset:13888
	v_cvt_pk_bf16_f32 v130, v10, v11
	v_cvt_pk_bf16_f32 v131, v12, v13
	v_cvt_pk_bf16_f32 v132, v14, v15
	v_cvt_pk_bf16_f32 v133, v16, v17
	ds_write_b128 v0, v[130:133] offset:16128
	v_cvt_pk_bf16_f32 v130, v2, v3
	v_cvt_pk_bf16_f32 v131, v4, v5
	v_cvt_pk_bf16_f32 v132, v6, v7
	v_cvt_pk_bf16_f32 v133, v8, v9
	ds_write_b128 v0, v[130:133] offset:16192
	v_and_b32_e32 v0, 0xffffff80, v136
	v_add_u32_e32 v130, s48, v0
	v_ashrrev_i32_e32 v131, 31, v130
	v_lshlrev_b64 v[130:131], 11, v[130:131]
	v_lshl_add_u64 v[130:131], s[38:39], 0, v[130:131]
	v_and_b32_e32 v0, 64, v136
	v_lshl_add_u64 v[130:131], s[46:47], 1, v[130:131]
	v_lshlrev_b32_e32 v0, 1, v0
	v_lshl_add_u64 v[138:139], v[130:131], 0, v[0:1]
	v_lshlrev_b32_e32 v0, 4, v136
	v_and_b32_e32 v0, 0x70, v0
	v_bfe_u32 v140, v136, 3, 3
	v_or_b32_e32 v130, v137, v0
	s_waitcnt lgkmcnt(0)
	v_mad_u32_u24 v137, v140, s4, v130
	ds_read_b128 v[130:133], v137
	v_lshl_add_u64 v[138:139], v[138:139], 0, v[0:1]
	v_lshlrev_b32_e32 v0, 11, v140
	v_lshl_add_u64 v[140:141], v[138:139], 0, v[0:1]
	s_mov_b64 s[50:51], 0
	s_waitcnt lgkmcnt(0)
	global_store_dwordx4 v[140:141], v[130:133], off
	ds_read_b128 v[130:133], v137 offset:1152
	v_or_b32_e32 v140, 0x4000, v0
	v_mov_b32_e32 v141, v1
	v_lshl_add_u64 v[140:141], v[138:139], 0, v[140:141]
	s_waitcnt lgkmcnt(0)
	global_store_dwordx4 v[140:141], v[130:133], off
	ds_read_b128 v[130:133], v137 offset:2304
	v_or_b32_e32 v140, 0x8000, v0
	v_mov_b32_e32 v141, v1
	v_lshl_add_u64 v[140:141], v[138:139], 0, v[140:141]
	s_waitcnt lgkmcnt(0)
	global_store_dwordx4 v[140:141], v[130:133], off
	ds_read_b128 v[130:133], v137 offset:3456
	v_or_b32_e32 v140, 0xc000, v0
	v_mov_b32_e32 v141, v1
	v_lshl_add_u64 v[140:141], v[138:139], 0, v[140:141]
	s_waitcnt lgkmcnt(0)
	global_store_dwordx4 v[140:141], v[130:133], off
	ds_read_b128 v[130:133], v137 offset:4608
	v_or_b32_e32 v140, 0x10000, v0
	v_mov_b32_e32 v141, v1
	v_lshl_add_u64 v[140:141], v[138:139], 0, v[140:141]
	s_waitcnt lgkmcnt(0)
	global_store_dwordx4 v[140:141], v[130:133], off
	ds_read_b128 v[130:133], v137 offset:5760
	v_or_b32_e32 v140, 0x14000, v0
	v_mov_b32_e32 v141, v1
	v_lshl_add_u64 v[140:141], v[138:139], 0, v[140:141]
	s_waitcnt lgkmcnt(0)
	global_store_dwordx4 v[140:141], v[130:133], off
	ds_read_b128 v[130:133], v137 offset:6912
	v_or_b32_e32 v140, 0x18000, v0
	v_mov_b32_e32 v141, v1
	v_lshl_add_u64 v[140:141], v[138:139], 0, v[140:141]
	s_waitcnt lgkmcnt(0)
	global_store_dwordx4 v[140:141], v[130:133], off
	ds_read_b128 v[130:133], v137 offset:8064
	v_or_b32_e32 v140, 0x1c000, v0
	v_mov_b32_e32 v141, v1
	v_lshl_add_u64 v[140:141], v[138:139], 0, v[140:141]
	s_waitcnt lgkmcnt(0)
	global_store_dwordx4 v[140:141], v[130:133], off
	ds_read_b128 v[130:133], v137 offset:9216
	v_or_b32_e32 v140, 0x20000, v0
	v_mov_b32_e32 v141, v1
	v_lshl_add_u64 v[140:141], v[138:139], 0, v[140:141]
	s_waitcnt lgkmcnt(0)
	global_store_dwordx4 v[140:141], v[130:133], off
	ds_read_b128 v[130:133], v137 offset:10368
	v_or_b32_e32 v140, 0x24000, v0
	v_mov_b32_e32 v141, v1
	v_lshl_add_u64 v[140:141], v[138:139], 0, v[140:141]
	s_waitcnt lgkmcnt(0)
	global_store_dwordx4 v[140:141], v[130:133], off
	ds_read_b128 v[130:133], v137 offset:11520
	v_or_b32_e32 v140, 0x28000, v0
	v_mov_b32_e32 v141, v1
	v_lshl_add_u64 v[140:141], v[138:139], 0, v[140:141]
	s_waitcnt lgkmcnt(0)
	global_store_dwordx4 v[140:141], v[130:133], off
	ds_read_b128 v[130:133], v137 offset:12672
	v_or_b32_e32 v140, 0x2c000, v0
	v_mov_b32_e32 v141, v1
	v_lshl_add_u64 v[140:141], v[138:139], 0, v[140:141]
	s_waitcnt lgkmcnt(0)
	global_store_dwordx4 v[140:141], v[130:133], off
	ds_read_b128 v[130:133], v137 offset:13824
	v_or_b32_e32 v140, 0x30000, v0
	v_mov_b32_e32 v141, v1
	v_lshl_add_u64 v[140:141], v[138:139], 0, v[140:141]
	s_waitcnt lgkmcnt(0)
	global_store_dwordx4 v[140:141], v[130:133], off
	ds_read_b128 v[130:133], v137 offset:14976
	v_or_b32_e32 v140, 0x34000, v0
	v_mov_b32_e32 v141, v1
	v_lshl_add_u64 v[140:141], v[138:139], 0, v[140:141]
	s_waitcnt lgkmcnt(0)
	global_store_dwordx4 v[140:141], v[130:133], off
	ds_read_b128 v[130:133], v137 offset:16128
	v_or_b32_e32 v140, 0x38000, v0
	v_mov_b32_e32 v141, v1
	v_lshl_add_u64 v[140:141], v[138:139], 0, v[140:141]
	v_or_b32_e32 v0, 0x3c000, v0
	s_waitcnt lgkmcnt(0)
	global_store_dwordx4 v[140:141], v[130:133], off
	ds_read_b128 v[130:133], v137 offset:17280
	v_lshl_add_u64 v[138:139], v[138:139], 0, v[0:1]
	s_waitcnt lgkmcnt(0)
	global_store_dwordx4 v[138:139], v[130:133], off
	s_waitcnt lgkmcnt(0)
	s_barrier
